# attention: relative-bias LDS table built once per layer per workgroup (second attention item reuses it)
# speedup vs baseline: 1.0091x; 1.0091x over previous
.LBB0_536:
	s_cmpk_gt_i32 s57, 0x7f
	s_mov_b64 s[0:1], -1
	s_cbranch_scc0 .LBB0_585
	s_and_b32 s8, s57, 7
	s_lshl_b32 s0, s8, 2
	v_mov_b32_e32 v2, v194
	v_mov_b32_e32 v1, s0
	global_load_dword v149, v0, s[80:81]
	s_barrier
	global_load_dword v4, v1, s[38:39] offset:480
	s_movk_i32 s0, 0x140
	v_cmp_gt_i32_e32 vcc, s0, v2
	s_cmpk_gt_i32 s57, 0x17f
	s_cbranch_scc0 .Lbt_do
	s_mov_b64 s[4:5], exec
	s_branch .LBB0_555
.Lbt_do:
	s_and_saveexec_b64 s[4:5], vcc
	s_cbranch_execz .LBB0_555
	v_max_i32_e32 v1, 0xffffff40, v2
	v_sub_u32_e32 v1, v1, v2
	v_add_u32_e32 v1, 0x1ff, v1
	s_movk_i32 s0, 0x1ff
	v_cmp_lt_u32_e32 vcc, s0, v1
	s_mov_b64 s[0:1], -1
	v_mov_b32_e32 v3, v2
	s_and_saveexec_b64 s[6:7], vcc
	s_cbranch_execz .LBB0_542
	v_lshrrev_b32_e32 v1, 9, v1
	v_add_u32_e32 v1, 1, v1
	v_and_b32_e32 v8, 0xfffffe, v1
	v_add_u32_e32 v3, 0x200, v2
	s_mov_b32 s10, s8
	s_waitcnt vmcnt(0)
	v_mov_b32_e32 v5, v4
	v_lshl_add_u32 v9, v2, 2, v201
	s_mov_b64 s[50:51], 0
	v_mov_b32_e32 v10, v8
	v_mov_b64_e32 v[6:7], v[2:3]
